# logical workgroup id = permuted hardware id (slot j -> (j>>1)+16*(j&1), XCD lane kept): the 116 workgroups of the partial in-proj round are every other hardware slot of each XCD
# baseline (speedup 1.0000x reference)
; #define LAS __attribute__((address_space(3)))
; __device__ __forceinline__ unsigned xb_add(unsigned* p, unsigned v) { return __hip_atomic_fetch_add(p, v, __ATOMIC_RELAXED, __HIP_MEMORY_SCOPE_AGENT); }
; __device__ __forceinline__ unsigned xb_xcc_id() { return (unsigned)__builtin_amdgcn_s_getreg((3 << 11) | 20) & 0xFu; }
; __device__ __forceinline__ XcdBarrier xcd_barrier_post(unsigned* bar, volatile LAS unsigned* st) {
;     XcdBarrier b; b.bar = bar; b.x = xb_xcc_id(); b.st = st;
;     if (threadIdx.x == 0) (void)xb_add(&bar[XB_XCNT(b.x)], 1u);
;     return b;
; __global__ void __launch_bounds__(512, 2) fwd_megakernel(Args a) {
;     extern __shared__ __attribute__((aligned(16))) unsigned char lds_raw[];
;     LAS unsigned char* lds = (LAS unsigned char*)lds_raw;
;     cg::grid_group grid = cg::this_grid();
;     const int bid = blockIdx.x, G = gridDim.x;
;     if (threadIdx.x < 64) ((LAS unsigned*)(lds + 131072))[threadIdx.x] = 0u;
;     __syncthreads();
;     (void)xcd_barrier_post((unsigned*)(a.ws + WS_BAR), (volatile LAS unsigned*)(lds + 131072) + 8);
_Z14fwd_megakernel4Args:
	s_load_dwordx4 s[76:79], s[0:1], 0x80
	s_load_dwordx2 s[42:43], s[0:1], 0x90
	s_add_u32 s6, s0, 0x90
	v_and_b32_e32 v208, 0x3ff, v0
	s_mov_b32 s71, s2
	s_addc_u32 s7, s1, 0
	v_cmp_gt_u32_e32 vcc, 64, v208
	s_and_saveexec_b64 s[4:5], vcc
	v_lshl_add_u32 v1, v208, 2, 0
	v_add_u32_e32 v1, 0x20000, v1
	v_mov_b32_e32 v2, 0
	ds_write_b32 v1, v2
	s_or_b64 exec, exec, s[4:5]
	s_load_dword s2, s[0:1], 0x98
	s_waitcnt lgkmcnt(0)
	s_cmp_lg_u32 s42, 0x100
	s_cbranch_scc1 .Lperm_skip
	s_and_b32 s8, s71, 7
	s_lshr_b32 s9, s71, 3
	s_and_b32 s10, s9, 1
	s_lshr_b32 s9, s9, 1
	s_lshl_b32 s10, s10, 4
	s_or_b32 s9, s9, s10
	s_lshl_b32 s9, s9, 3
	s_or_b32 s71, s9, s8
.Lperm_skip:
	s_add_u32 s4, s78, 0x1700000
	s_addc_u32 s5, s79, 0
	v_writelane_b32 v253, s4, 0
	s_barrier
	s_nop 0
	v_writelane_b32 v253, s5, 1
	s_getreg_b32 s3, hwreg(HW_REG_XCC_ID, 0, 4)
	v_cmp_eq_u32_e64 s[8:9], 0, v208
	s_mov_b64 s[4:5], exec
	s_nop 0
	v_writelane_b32 v253, s8, 2
	s_nop 1
	v_writelane_b32 v253, s9, 3
	s_and_b64 s[8:9], s[4:5], s[8:9]
	s_mov_b64 exec, s[8:9]
	s_cbranch_execz .LBB0_5
	s_mov_b64 s[8:9], exec
	v_mbcnt_lo_u32_b32 v1, s8, 0
	v_mbcnt_hi_u32_b32 v1, s9, v1
	v_cmp_eq_u32_e32 vcc, 0, v1
	s_and_b64 s[10:11], exec, vcc
	s_mov_b64 exec, s[10:11]
	s_cbranch_execz .LBB0_5
	s_lshl_b32 s3, s3, 8
	s_bcnt1_i32_b64 s8, s[8:9]
	s_and_b32 s3, s3, 0xf00
	v_mov_b32_e32 v2, s8
	v_readlane_b32 s8, v253, 0
	v_mov_b32_e32 v1, s3
	v_readlane_b32 s9, v253, 1
	s_nop 4
	global_atomic_add v1, v2, s[8:9] offset:1024
